# attention: K LDS-DMA after the second QK MFMA pair
# speedup vs baseline: 1.0101x; 1.0022x over previous
; #define SBAR() __builtin_amdgcn_sched_barrier(0)
; #define KRD(A, B, d0) do { const int ad_ = (kc ^ ((d0) << 5)) + kbt; A = lds_rd128<0>(ad_); B = lds_rd128<8192>(ad_); } while (0)
; __device__ __forceinline__ float softmax_rel(f32x16& p0, f32x16& p1, bool first, float& m_reg, float& l_reg, bf16x8& pa0, bf16x8& pa1, bf16x8& pa2, bf16x8& pa3) {
;   float pmax = p0[0];
; #pragma unroll
;   for (int r = 1; r < 16; ++r) pmax = fmaxf(pmax, p0[r]);
; #pragma unroll
;   for (int r = 0; r < 16; ++r) pmax = fmaxf(pmax, p1[r]);
;   { auto rr = __builtin_amdgcn_permlane32_swap(__float_as_uint(pmax), __float_as_uint(pmax), false, false);
;     pmax = fmaxf(__uint_as_float(rr[0]), __uint_as_float(rr[1])); }
;   float alpha = 1.f;
;   if (__builtin_expect(first || __any(pmax > THR2), 0)) {
; __device__ __forceinline__ void qkt_pipe(f32x16& p0, f32x16& p1, int kbt, int kc, const bf16x8* qr, const f32x16& z) {
;   bf16x8 a0, b0, a1, b1, a2, b2, a3, b3;
;     ...
;   KRD(a0, b0, 0); KRD(a1, b1, 1); KRD(a2, b2, 2); KRD(a3, b3, 3);
;   KW(6); p0 = __builtin_amdgcn_mfma_f32_32x32x16_bf16(a0, qr[0], z, 0, 0, 0);  p1 = __builtin_amdgcn_mfma_f32_32x32x16_bf16(b0, qr[0], z, 0, 0, 0);  SBAR(); KRD(a0, b0, 4);
;   KW(6); p0 = __builtin_amdgcn_mfma_f32_32x32x16_bf16(a1, qr[1], p0, 0, 0, 0); p1 = __builtin_amdgcn_mfma_f32_32x32x16_bf16(b1, qr[1], p1, 0, 0, 0); SBAR(); KRD(a1, b1, 5);
;   KW(6); p0 = __builtin_amdgcn_mfma_f32_32x32x16_bf16(a2, qr[2], p0, 0, 0, 0); p1 = __builtin_amdgcn_mfma_f32_32x32x16_bf16(b2, qr[2], p1, 0, 0, 0); SBAR(); KRD(a2, b2, 6);
;   KW(6); p0 = __builtin_amdgcn_mfma_f32_32x32x16_bf16(a3, qr[3], p0, 0, 0, 0); p1 = __builtin_amdgcn_mfma_f32_32x32x16_bf16(b3, qr[3], p1, 0, 0, 0); SBAR(); KRD(a3, b3, 7);
;   KW(6); p0 = __builtin_amdgcn_mfma_f32_32x32x16_bf16(a0, qr[4], p0, 0, 0, 0); p1 = __builtin_amdgcn_mfma_f32_32x32x16_bf16(b0, qr[4], p1, 0, 0, 0); SBAR();
;   KW(4); p0 = __builtin_amdgcn_mfma_f32_32x32x16_bf16(a1, qr[5], p0, 0, 0, 0); p1 = __builtin_amdgcn_mfma_f32_32x32x16_bf16(b1, qr[5], p1, 0, 0, 0); SBAR();
;   KW(2); p0 = __builtin_amdgcn_mfma_f32_32x32x16_bf16(a2, qr[6], p0, 0, 0, 0); p1 = __builtin_amdgcn_mfma_f32_32x32x16_bf16(b2, qr[6], p1, 0, 0, 0); SBAR();
;   KW(0); p0 = __builtin_amdgcn_mfma_f32_32x32x16_bf16(a3, qr[7], p0, 0, 0, 0); p1 = __builtin_amdgcn_mfma_f32_32x32x16_bf16(b3, qr[7], p1, 0, 0, 0);
.LBB0_348:
	s_mov_b32 s11, s24
	s_setprio 2
	v_lshl_add_u32 v212, s11, 14, v199
	v_add_u32_e32 v144, v212, v213
	ds_read_b128 v[194:197], v144 offset:0
	ds_read_b128 v[226:229], v144 offset:0x2000
	v_xor_b32_e32 v144, 32, v213
	v_add_u32_e32 v144, v212, v144
	ds_read_b128 v[230:233], v144 offset:0
	ds_read_b128 v[234:237], v144 offset:0x2000
	v_xor_b32_e32 v144, 64, v213
	v_add_u32_e32 v144, v212, v144
	ds_read_b128 v[238:241], v144 offset:0
	ds_read_b128 v[242:245], v144 offset:0x2000
	v_xor_b32_e32 v144, 0x60, v213
	v_add_u32_e32 v144, v212, v144
	ds_read_b128 v[246:249], v144 offset:0
	ds_read_b128 v[214:217], v144 offset:0x2000
	s_add_i32 s12, s10, 2
	s_cmp_lt_u32 s12, s74
	s_cselect_b64 s[56:57], -1, 0
	s_cmp_ge_u32 s12, s74
	s_cselect_b64 s[90:91], -1, 0
	s_and_b64 vcc, exec, s[90:91]
	v_xor_b32_e32 v128, 0x80000000, v224
	v_mov_b32_e32 v129, v128
	v_mov_b32_e32 v130, v128
	v_mov_b32_e32 v131, v128
	v_mov_b32_e32 v132, v128
	v_mov_b32_e32 v133, v128
	v_mov_b32_e32 v134, v128
	v_mov_b32_e32 v135, v128
	v_mov_b32_e32 v136, v128
	v_mov_b32_e32 v137, v128
	v_mov_b32_e32 v138, v128
	v_mov_b32_e32 v139, v128
	v_mov_b32_e32 v140, v128
	v_mov_b32_e32 v141, v128
	v_mov_b32_e32 v142, v128
	v_mov_b32_e32 v143, v128
	s_waitcnt lgkmcnt(6)
	s_nop 1
	v_mfma_f32_32x32x16_bf16 v[144:159], v[194:197], v[188:191], v[128:143]
	v_mfma_f32_32x32x16_bf16 v[128:143], v[226:229], v[188:191], v[128:143]
	v_xor_b32_e32 v194, 0x80, v213
	v_add_u32_e32 v220, v212, v194
	ds_read_b128 v[194:197], v220 offset:0
	ds_read_b128 v[226:229], v220 offset:0x2000
	s_waitcnt lgkmcnt(6)
	v_mfma_f32_32x32x16_bf16 v[144:159], v[230:233], v[184:187], v[144:159]
	v_mfma_f32_32x32x16_bf16 v[128:143], v[234:237], v[184:187], v[128:143]
	v_xor_b32_e32 v220, 0xa0, v213
	v_add_u32_e32 v220, v212, v220
	ds_read_b128 v[230:233], v220 offset:0
	ds_read_b128 v[234:237], v220 offset:0x2000
	s_cbranch_vccnz .Lq0_nodma
	s_add_u32 s24, s38, 0xfffff000
	s_addc_u32 s25, s39, -1
	s_lshl_b32 s12, s9, 14
	s_add_i32 s12, s12, s0
	s_mov_b32 s13, m0
	s_mov_b32 m0, s12
	s_nop 0
	global_load_lds_dwordx4 v192, s[24:25]
	s_addk_i32 s12, 0x400
	s_mov_b32 m0, s12
	s_nop 0
	global_load_lds_dwordx4 v202, s[24:25]
	s_mov_b32 m0, s13
.Lq0_nodma:
	s_waitcnt lgkmcnt(6)
	v_mfma_f32_32x32x16_bf16 v[144:159], v[238:241], v[180:183], v[144:159]
	v_mfma_f32_32x32x16_bf16 v[128:143], v[242:245], v[180:183], v[128:143]
	v_xor_b32_e32 v220, 0xc0, v213
	v_add_u32_e32 v220, v212, v220
	ds_read_b128 v[238:241], v220 offset:0
	ds_read_b128 v[242:245], v220 offset:0x2000
	s_waitcnt lgkmcnt(6)
	v_mfma_f32_32x32x16_bf16 v[144:159], v[246:249], v[176:179], v[144:159]
	v_mfma_f32_32x32x16_bf16 v[128:143], v[214:217], v[176:179], v[128:143]
	v_xor_b32_e32 v214, 0xe0, v213
	v_add_u32_e32 v212, v212, v214
	ds_read_b128 v[214:217], v212 offset:0
	ds_read_b128 v[246:249], v212 offset:0x2000
	s_waitcnt lgkmcnt(6)
	v_mfma_f32_32x32x16_bf16 v[144:159], v[194:197], v[172:175], v[144:159]
	v_mfma_f32_32x32x16_bf16 v[128:143], v[226:229], v[172:175], v[128:143]
	s_waitcnt lgkmcnt(4)
	v_mfma_f32_32x32x16_bf16 v[144:159], v[230:233], v[168:171], v[144:159]
	v_mfma_f32_32x32x16_bf16 v[128:143], v[234:237], v[168:171], v[128:143]
	s_waitcnt lgkmcnt(2)
	v_mfma_f32_32x32x16_bf16 v[144:159], v[238:241], v[164:167], v[144:159]
	v_mfma_f32_32x32x16_bf16 v[128:143], v[242:245], v[164:167], v[128:143]
	s_waitcnt lgkmcnt(0)
	v_mfma_f32_32x32x16_bf16 v[144:159], v[214:217], v[160:163], v[144:159]
	s_cmp_eq_u32 s10, 0
	s_cselect_b64 s[62:63], -1, 0
	s_cmp_lg_u32 s10, 0
	v_mfma_f32_32x32x16_bf16 v[128:143], v[246:249], v[160:163], v[128:143]
	s_nop 7
	v_max_f32_e32 v194, v145, v145
	v_max_f32_e32 v195, v144, v144
	v_max_f32_e32 v194, v195, v194
	v_max3_f32 v194, v194, v146, v147
	v_max3_f32 v194, v194, v148, v149
	v_max3_f32 v195, v128, v129, v130
	v_max3_f32 v194, v194, v150, v151
	v_max3_f32 v195, v195, v131, v132
	v_max3_f32 v194, v194, v152, v153
	v_max3_f32 v195, v195, v133, v134
	v_max3_f32 v194, v194, v154, v155
	v_max3_f32 v195, v195, v135, v136
	v_max3_f32 v194, v194, v156, v157
	v_max3_f32 v195, v195, v137, v138
	v_max3_f32 v194, v194, v158, v159
	v_max3_f32 v195, v195, v139, v140
	v_max3_f32 v195, v195, v141, v142
	v_max3_f32 v194, v194, v195, v143
	v_mov_b32_e32 v195, v194
	s_nop 1
	v_permlane32_swap_b32_e32 v194, v195
	v_max_f32_e32 v195, v195, v195
	v_max_f32_e32 v194, v194, v194
	v_max_f32_e32 v226, v194, v195
	s_cbranch_scc0 .LBB0_371
	v_cmp_lt_f32_e32 vcc, s30, v226
	s_cbranch_vccnz .Lm0_rare
	v_mov_b32_e32 v226, 1.0

; #define SBAR() __builtin_amdgcn_sched_barrier(0)
; #define KRD(A, B, d0) do { const int ad_ = (kc ^ ((d0) << 5)) + kbt; A = lds_rd128<0>(ad_); B = lds_rd128<8192>(ad_); } while (0)
; __device__ __forceinline__ float softmax_rel(f32x16& p0, f32x16& p1, bool first, float& m_reg, float& l_reg, bf16x8& pa0, bf16x8& pa1, bf16x8& pa2, bf16x8& pa3) {
;   float pmax = p0[0];
; #pragma unroll
;   for (int r = 1; r < 16; ++r) pmax = fmaxf(pmax, p0[r]);
; #pragma unroll
;   for (int r = 0; r < 16; ++r) pmax = fmaxf(pmax, p1[r]);
;   { auto rr = __builtin_amdgcn_permlane32_swap(__float_as_uint(pmax), __float_as_uint(pmax), false, false);
;     pmax = fmaxf(__uint_as_float(rr[0]), __uint_as_float(rr[1])); }
;   float alpha = 1.f;
;   if (__builtin_expect(first || __any(pmax > THR2), 0)) {
; __device__ __forceinline__ void qkt_pipe(f32x16& p0, f32x16& p1, int kbt, int kc, const bf16x8* qr, const f32x16& z) {
;   bf16x8 a0, b0, a1, b1, a2, b2, a3, b3;
;     ...
;   KRD(a0, b0, 0); KRD(a1, b1, 1); KRD(a2, b2, 2); KRD(a3, b3, 3);
;   KW(6); p0 = __builtin_amdgcn_mfma_f32_32x32x16_bf16(a0, qr[0], z, 0, 0, 0);  p1 = __builtin_amdgcn_mfma_f32_32x32x16_bf16(b0, qr[0], z, 0, 0, 0);  SBAR(); KRD(a0, b0, 4);
;   KW(6); p0 = __builtin_amdgcn_mfma_f32_32x32x16_bf16(a1, qr[1], p0, 0, 0, 0); p1 = __builtin_amdgcn_mfma_f32_32x32x16_bf16(b1, qr[1], p1, 0, 0, 0); SBAR(); KRD(a1, b1, 5);
;   KW(6); p0 = __builtin_amdgcn_mfma_f32_32x32x16_bf16(a2, qr[2], p0, 0, 0, 0); p1 = __builtin_amdgcn_mfma_f32_32x32x16_bf16(b2, qr[2], p1, 0, 0, 0); SBAR(); KRD(a2, b2, 6);
;   KW(6); p0 = __builtin_amdgcn_mfma_f32_32x32x16_bf16(a3, qr[3], p0, 0, 0, 0); p1 = __builtin_amdgcn_mfma_f32_32x32x16_bf16(b3, qr[3], p1, 0, 0, 0); SBAR(); KRD(a3, b3, 7);
;   KW(6); p0 = __builtin_amdgcn_mfma_f32_32x32x16_bf16(a0, qr[4], p0, 0, 0, 0); p1 = __builtin_amdgcn_mfma_f32_32x32x16_bf16(b0, qr[4], p1, 0, 0, 0); SBAR();
;   KW(4); p0 = __builtin_amdgcn_mfma_f32_32x32x16_bf16(a1, qr[5], p0, 0, 0, 0); p1 = __builtin_amdgcn_mfma_f32_32x32x16_bf16(b1, qr[5], p1, 0, 0, 0); SBAR();
;   KW(2); p0 = __builtin_amdgcn_mfma_f32_32x32x16_bf16(a2, qr[6], p0, 0, 0, 0); p1 = __builtin_amdgcn_mfma_f32_32x32x16_bf16(b2, qr[6], p1, 0, 0, 0); SBAR();
;   KW(0); p0 = __builtin_amdgcn_mfma_f32_32x32x16_bf16(a3, qr[7], p0, 0, 0, 0); p1 = __builtin_amdgcn_mfma_f32_32x32x16_bf16(b3, qr[7], p1, 0, 0, 0);
.LBB0_381:
	s_mov_b32 s10, s11
	s_setprio 2
	v_lshl_add_u32 v212, s10, 14, v201
	v_add_u32_e32 v144, v212, v225
	ds_read_b128 v[194:197], v144 offset:0
	ds_read_b128 v[214:217], v144 offset:0x2000
	v_xor_b32_e32 v144, 32, v225
	v_add_u32_e32 v144, v212, v144
	ds_read_b128 v[230:233], v144 offset:0
	ds_read_b128 v[234:237], v144 offset:0x2000
	v_xor_b32_e32 v144, 64, v225
	v_add_u32_e32 v144, v212, v144
	ds_read_b128 v[238:241], v144 offset:0
	ds_read_b128 v[242:245], v144 offset:0x2000
	v_xor_b32_e32 v144, 0x60, v225
	v_add_u32_e32 v144, v212, v144
	ds_read_b128 v[246:249], v144 offset:0
	ds_read_b128 v[220:223], v144 offset:0x2000
	s_add_i32 s11, s9, 2
	s_cmp_lt_u32 s11, s74
	s_cselect_b64 s[52:53], -1, 0
	s_cmp_ge_u32 s11, s74
	s_cselect_b64 s[50:51], -1, 0
	s_and_b64 vcc, exec, s[50:51]
	v_xor_b32_e32 v128, 0x80000000, v227
	v_mov_b32_e32 v129, v128
	v_mov_b32_e32 v130, v128
	v_mov_b32_e32 v131, v128
	v_mov_b32_e32 v132, v128
	v_mov_b32_e32 v133, v128
	v_mov_b32_e32 v134, v128
	v_mov_b32_e32 v135, v128
	v_mov_b32_e32 v136, v128
	v_mov_b32_e32 v137, v128
	v_mov_b32_e32 v138, v128
	v_mov_b32_e32 v139, v128
	v_mov_b32_e32 v140, v128
	v_mov_b32_e32 v141, v128
	v_mov_b32_e32 v142, v128
	v_mov_b32_e32 v143, v128
	s_waitcnt lgkmcnt(6)
	s_nop 1
	v_mfma_f32_32x32x16_bf16 v[144:159], v[194:197], v[188:191], v[128:143]
	v_mfma_f32_32x32x16_bf16 v[128:143], v[214:217], v[188:191], v[128:143]
	v_xor_b32_e32 v194, 0x80, v225
	v_add_u32_e32 v229, v212, v194
	ds_read_b128 v[194:197], v229 offset:0
	ds_read_b128 v[214:217], v229 offset:0x2000
	s_waitcnt lgkmcnt(6)
	v_mfma_f32_32x32x16_bf16 v[144:159], v[230:233], v[184:187], v[144:159]
	v_mfma_f32_32x32x16_bf16 v[128:143], v[234:237], v[184:187], v[128:143]
	v_xor_b32_e32 v229, 0xa0, v225
	v_add_u32_e32 v229, v212, v229
	ds_read_b128 v[230:233], v229 offset:0
	ds_read_b128 v[234:237], v229 offset:0x2000
	s_cbranch_vccnz .Lq1_nodma
	s_add_u32 s24, s60, 0xfffff100
	s_addc_u32 s25, s61, -1
	s_lshl_b32 s11, s7, 14
	s_add_i32 s11, s11, s0
	s_mov_b32 s12, m0
	s_mov_b32 m0, s11
	s_nop 0
	global_load_lds_dwordx4 v192, s[24:25]
	s_addk_i32 s11, 0x400
	s_mov_b32 m0, s11
	s_nop 0
	global_load_lds_dwordx4 v202, s[24:25]
	s_mov_b32 m0, s12
.Lq1_nodma:
	s_waitcnt lgkmcnt(6)
	v_mfma_f32_32x32x16_bf16 v[144:159], v[238:241], v[180:183], v[144:159]
	v_mfma_f32_32x32x16_bf16 v[128:143], v[242:245], v[180:183], v[128:143]
	v_xor_b32_e32 v229, 0xc0, v225
	v_add_u32_e32 v229, v212, v229
	ds_read_b128 v[238:241], v229 offset:0
	ds_read_b128 v[242:245], v229 offset:0x2000
	s_waitcnt lgkmcnt(6)
	v_mfma_f32_32x32x16_bf16 v[144:159], v[246:249], v[176:179], v[144:159]
	v_mfma_f32_32x32x16_bf16 v[128:143], v[220:223], v[176:179], v[128:143]
	v_xor_b32_e32 v220, 0xe0, v225
	v_add_u32_e32 v212, v212, v220
	ds_read_b128 v[220:223], v212 offset:0
	ds_read_b128 v[246:249], v212 offset:0x2000
	s_waitcnt lgkmcnt(6)
	v_mfma_f32_32x32x16_bf16 v[144:159], v[194:197], v[172:175], v[144:159]
	v_mfma_f32_32x32x16_bf16 v[128:143], v[214:217], v[172:175], v[128:143]
	s_waitcnt lgkmcnt(4)
	v_mfma_f32_32x32x16_bf16 v[144:159], v[230:233], v[168:171], v[144:159]
	v_mfma_f32_32x32x16_bf16 v[128:143], v[234:237], v[168:171], v[128:143]
	s_waitcnt lgkmcnt(2)
	v_mfma_f32_32x32x16_bf16 v[144:159], v[238:241], v[164:167], v[144:159]
	v_mfma_f32_32x32x16_bf16 v[128:143], v[242:245], v[164:167], v[128:143]
	s_waitcnt lgkmcnt(0)
	v_mfma_f32_32x32x16_bf16 v[144:159], v[220:223], v[160:163], v[144:159]
	s_cmp_eq_u32 s9, 0
	s_cselect_b64 s[56:57], -1, 0
	s_cmp_lg_u32 s9, 0
	v_mfma_f32_32x32x16_bf16 v[128:143], v[246:249], v[160:163], v[128:143]
	s_nop 7
	v_max_f32_e32 v194, v145, v145
	v_max_f32_e32 v195, v144, v144
	v_max_f32_e32 v194, v195, v194
	v_max3_f32 v194, v194, v146, v147
	v_max3_f32 v194, v194, v148, v149
	v_max3_f32 v195, v128, v129, v130
	v_max3_f32 v194, v194, v150, v151
	v_max3_f32 v195, v195, v131, v132
	v_max3_f32 v194, v194, v152, v153
	v_max3_f32 v195, v195, v133, v134
	v_max3_f32 v194, v194, v154, v155
	v_max3_f32 v195, v195, v135, v136
	v_max3_f32 v194, v194, v156, v157
	v_max3_f32 v195, v195, v137, v138
	v_max3_f32 v194, v194, v158, v159
	v_max3_f32 v195, v195, v139, v140
	v_max3_f32 v195, v195, v141, v142
	v_max3_f32 v194, v194, v195, v143
	v_mov_b32_e32 v195, v194
	s_nop 1
	v_permlane32_swap_b32_e32 v194, v195
	v_max_f32_e32 v195, v195, v195
	v_max_f32_e32 v194, v194, v194
	v_max_f32_e32 v229, v194, v195
	s_cbranch_scc0 .LBB0_404
	v_cmp_lt_f32_e32 vcc, s30, v229
	s_cbranch_vccnz .Lm1_rare
	v_mov_b32_e32 v229, 1.0
